# v46 + write-through on the P9 (FFN2 gate/up) activation stores
# baseline (speedup 1.0000x reference)
.LBB0_1942:
	v_lshl_add_u32 v131, s82, 10, v220
	ds_read2_b32 v[134:135], v131 offset1:16
	v_lshl_or_b32 v132, s83, 7, v219
	v_lshl_add_u32 v130, s40, 8, v1
	v_ashrrev_i32_e32 v133, 31, v132
	s_andn2_b64 vcc, exec, s[36:37]
	s_waitcnt lgkmcnt(0)
	v_pk_mul_f32 v[122:123], v[122:123], v[134:135] op_sel_hi:[1,0]
	v_pk_mul_f32 v[126:127], v[126:127], v[134:135] op_sel_hi:[1,0]
	v_mul_f32_e32 v136, 0xbfb8aa3b, v122
	v_mul_f32_e32 v137, 0xbfb8aa3b, v123
	v_exp_f32_e32 v136, v136
	v_exp_f32_e32 v137, v137
	v_pk_mul_f32 v[124:125], v[124:125], v[134:135] op_sel_hi:[1,0]
	v_pk_mul_f32 v[114:115], v[114:115], v[134:135] op_sel_hi:[1,0]
	v_add_f32_e32 v136, 1.0, v136
	v_add_f32_e32 v137, 1.0, v137
	v_rcp_f32_e32 v136, v136
	v_rcp_f32_e32 v137, v137
	v_pk_mul_f32 v[118:119], v[118:119], v[134:135] op_sel_hi:[1,0]
	v_pk_mul_f32 v[116:117], v[116:117], v[134:135] op_sel_hi:[1,0]
	v_pk_mul_f32 v[120:121], v[120:121], v[134:135] op_sel_hi:[1,0]
	v_pk_mul_f32 v[122:123], v[122:123], v[136:137]
	v_pk_mul_f32 v[128:129], v[128:129], v[134:135] op_sel_hi:[1,0]
	v_pk_mul_f32 v[122:123], v[126:127], v[122:123]
	v_mul_f32_e32 v126, 0xbfb8aa3b, v124
	v_mul_f32_e32 v127, 0xbfb8aa3b, v125
	v_exp_f32_e32 v126, v126
	v_exp_f32_e32 v127, v127
	v_add_f32_e32 v126, 1.0, v126
	v_add_f32_e32 v127, 1.0, v127
	v_rcp_f32_e32 v126, v126
	v_rcp_f32_e32 v127, v127
	s_nop 0
	v_pk_mul_f32 v[124:125], v[124:125], v[126:127]
	v_mul_f32_e32 v126, 0xbfb8aa3b, v114
	v_mul_f32_e32 v127, 0xbfb8aa3b, v115
	v_exp_f32_e32 v126, v126
	v_exp_f32_e32 v127, v127
	v_pk_mul_f32 v[124:125], v[128:129], v[124:125]
	v_add_f32_e32 v126, 1.0, v126
	v_add_f32_e32 v127, 1.0, v127
	v_rcp_f32_e32 v126, v126
	v_rcp_f32_e32 v127, v127
	s_nop 0
	v_pk_mul_f32 v[114:115], v[114:115], v[126:127]
	s_nop 0
	v_pk_mul_f32 v[114:115], v[118:119], v[114:115]
	v_mul_f32_e32 v118, 0xbfb8aa3b, v116
	v_mul_f32_e32 v119, 0xbfb8aa3b, v117
	v_exp_f32_e32 v118, v118
	v_exp_f32_e32 v119, v119
	v_add_f32_e32 v118, 1.0, v118
	v_add_f32_e32 v119, 1.0, v119
	v_rcp_f32_e32 v118, v118
	v_rcp_f32_e32 v119, v119
	s_nop 0
	v_pk_mul_f32 v[116:117], v[116:117], v[118:119]
	s_nop 0
	v_pk_mul_f32 v[116:117], v[120:121], v[116:117]
	v_cvt_pk_bf16_f32 v120, v114, v115
	v_mov_b64_e32 v[114:115], s[54:55]
	v_cvt_pk_bf16_f32 v118, v122, v123
	v_cvt_pk_bf16_f32 v121, v116, v117
	v_mad_i64_i32 v[122:123], s[14:15], v130, s73, v[114:115]
	v_lshlrev_b64 v[116:117], 1, v[132:133]
	v_cvt_pk_bf16_f32 v119, v124, v125
	v_lshl_add_u64 v[122:123], v[122:123], 0, v[116:117]
	global_store_dwordx4 v[122:123], v[118:121], off sc0 sc1
	s_nop 1
	v_mov_b32_e32 v118, v135
	v_pk_mul_f32 v[106:107], v[106:107], v[118:119] op_sel_hi:[1,0]
	s_nop 0
	v_mul_f32_e32 v119, 0xbfb8aa3b, v106
	v_exp_f32_e32 v119, v119
	s_nop 0
	v_add_f32_e32 v119, 1.0, v119
	v_rcp_f32_e32 v120, v119
	v_pk_mul_f32 v[110:111], v[110:111], v[118:119] op_sel_hi:[1,0]
	v_mul_f32_e32 v119, 0xbfb8aa3b, v107
	v_exp_f32_e32 v119, v119
	s_nop 0
	v_add_f32_e32 v119, 1.0, v119
	v_rcp_f32_e32 v121, v119
	v_pk_mul_f32 v[108:109], v[108:109], v[118:119] op_sel_hi:[1,0]
	v_pk_mul_f32 v[98:99], v[98:99], v[118:119] op_sel_hi:[1,0]
	v_pk_mul_f32 v[102:103], v[102:103], v[118:119] op_sel_hi:[1,0]
	v_pk_mul_f32 v[106:107], v[106:107], v[120:121]
	v_pk_mul_f32 v[112:113], v[112:113], v[118:119] op_sel_hi:[1,0]
	v_pk_mul_f32 v[106:107], v[110:111], v[106:107]
	v_mul_f32_e32 v110, 0xbfb8aa3b, v108
	v_mul_f32_e32 v111, 0xbfb8aa3b, v109
	v_exp_f32_e32 v110, v110
	v_exp_f32_e32 v111, v111
	v_pk_mul_f32 v[104:105], v[104:105], v[118:119] op_sel_hi:[1,0]
	v_add_f32_e32 v110, 1.0, v110
	v_add_f32_e32 v111, 1.0, v111
	v_rcp_f32_e32 v110, v110
	v_rcp_f32_e32 v111, v111
	s_nop 0
	v_pk_mul_f32 v[108:109], v[108:109], v[110:111]
	v_mul_f32_e32 v110, 0xbfb8aa3b, v98
	v_mul_f32_e32 v111, 0xbfb8aa3b, v99
	v_exp_f32_e32 v110, v110
	v_exp_f32_e32 v111, v111
	v_pk_mul_f32 v[108:109], v[112:113], v[108:109]
	v_add_f32_e32 v110, 1.0, v110
	v_add_f32_e32 v111, 1.0, v111
	v_rcp_f32_e32 v110, v110
	v_rcp_f32_e32 v111, v111
	s_nop 0
	v_pk_mul_f32 v[98:99], v[98:99], v[110:111]
	s_nop 0
	v_pk_mul_f32 v[102:103], v[102:103], v[98:99]
	v_pk_mul_f32 v[98:99], v[100:101], v[118:119] op_sel_hi:[1,0]
	v_or_b32_e32 v110, 16, v130
	v_mul_f32_e32 v100, 0xbfb8aa3b, v98
	v_mul_f32_e32 v101, 0xbfb8aa3b, v99
	v_exp_f32_e32 v100, v100
	v_exp_f32_e32 v101, v101
	v_add_f32_e32 v100, 1.0, v100
	v_add_f32_e32 v101, 1.0, v101
	v_rcp_f32_e32 v100, v100
	v_rcp_f32_e32 v101, v101
	s_nop 0
	v_pk_mul_f32 v[98:99], v[98:99], v[100:101]
	s_nop 0
	v_pk_mul_f32 v[104:105], v[104:105], v[98:99]
	v_cvt_pk_bf16_f32 v100, v102, v103
	v_mad_i64_i32 v[102:103], s[14:15], v110, s73, v[114:115]
	v_cvt_pk_bf16_f32 v98, v106, v107
	v_cvt_pk_bf16_f32 v99, v108, v109
	v_cvt_pk_bf16_f32 v101, v104, v105
	v_lshl_add_u64 v[102:103], v[102:103], 0, v[116:117]
	global_store_dwordx4 v[102:103], v[98:101], off sc0 sc1
	ds_read2_b32 v[98:99], v131 offset0:32 offset1:48
	s_waitcnt lgkmcnt(0)
	v_pk_mul_f32 v[90:91], v[90:91], v[98:99] op_sel_hi:[1,0]
	s_nop 0
	v_mul_f32_e32 v100, 0xbfb8aa3b, v90
	v_mul_f32_e32 v101, 0xbfb8aa3b, v91
	v_exp_f32_e32 v100, v100
	v_exp_f32_e32 v101, v101
	v_pk_mul_f32 v[94:95], v[94:95], v[98:99] op_sel_hi:[1,0]
	v_pk_mul_f32 v[92:93], v[92:93], v[98:99] op_sel_hi:[1,0]
	v_add_f32_e32 v100, 1.0, v100
	v_add_f32_e32 v101, 1.0, v101
	v_rcp_f32_e32 v100, v100
	v_rcp_f32_e32 v101, v101
	v_pk_mul_f32 v[82:83], v[82:83], v[98:99] op_sel_hi:[1,0]
	v_pk_mul_f32 v[86:87], v[86:87], v[98:99] op_sel_hi:[1,0]
	v_pk_mul_f32 v[96:97], v[96:97], v[98:99] op_sel_hi:[1,0]
	v_pk_mul_f32 v[90:91], v[90:91], v[100:101]
	v_pk_mul_f32 v[88:89], v[88:89], v[98:99] op_sel_hi:[1,0]
	v_pk_mul_f32 v[90:91], v[94:95], v[90:91]
	v_mul_f32_e32 v94, 0xbfb8aa3b, v92
	v_mul_f32_e32 v95, 0xbfb8aa3b, v93
	v_exp_f32_e32 v94, v94
	v_exp_f32_e32 v95, v95
	v_add_f32_e32 v94, 1.0, v94
	v_add_f32_e32 v95, 1.0, v95
	v_rcp_f32_e32 v94, v94
	v_rcp_f32_e32 v95, v95
	s_nop 0
	v_pk_mul_f32 v[92:93], v[92:93], v[94:95]
	v_mul_f32_e32 v94, 0xbfb8aa3b, v82
	v_mul_f32_e32 v95, 0xbfb8aa3b, v83
	v_exp_f32_e32 v94, v94
	v_exp_f32_e32 v95, v95
	v_pk_mul_f32 v[92:93], v[96:97], v[92:93]
	v_add_f32_e32 v94, 1.0, v94
	v_add_f32_e32 v95, 1.0, v95
	v_rcp_f32_e32 v94, v94
	v_rcp_f32_e32 v95, v95
	s_nop 0
	v_pk_mul_f32 v[82:83], v[82:83], v[94:95]
	s_nop 0
	v_pk_mul_f32 v[86:87], v[86:87], v[82:83]
	v_pk_mul_f32 v[82:83], v[84:85], v[98:99] op_sel_hi:[1,0]
	v_or_b32_e32 v94, 32, v130
	v_mul_f32_e32 v84, 0xbfb8aa3b, v82
	v_mul_f32_e32 v85, 0xbfb8aa3b, v83
	v_exp_f32_e32 v84, v84
	v_exp_f32_e32 v85, v85
	v_add_f32_e32 v84, 1.0, v84
	v_add_f32_e32 v85, 1.0, v85
	v_rcp_f32_e32 v84, v84
	v_rcp_f32_e32 v85, v85
	s_nop 0
	v_pk_mul_f32 v[82:83], v[82:83], v[84:85]
	s_nop 0
	v_pk_mul_f32 v[88:89], v[88:89], v[82:83]
	v_cvt_pk_bf16_f32 v84, v86, v87
	v_mad_i64_i32 v[86:87], s[14:15], v94, s73, v[114:115]
	v_cvt_pk_bf16_f32 v82, v90, v91
	v_cvt_pk_bf16_f32 v83, v92, v93
	v_cvt_pk_bf16_f32 v85, v88, v89
	v_lshl_add_u64 v[86:87], v[86:87], 0, v[116:117]
	global_store_dwordx4 v[86:87], v[82:85], off sc0 sc1
	s_nop 1
	v_mov_b32_e32 v82, v99
	v_pk_mul_f32 v[74:75], v[74:75], v[82:83] op_sel_hi:[1,0]
	s_nop 0
	v_mul_f32_e32 v83, 0xbfb8aa3b, v74
	v_exp_f32_e32 v83, v83
	s_nop 0
	v_add_f32_e32 v83, 1.0, v83
	v_rcp_f32_e32 v84, v83
	v_pk_mul_f32 v[78:79], v[78:79], v[82:83] op_sel_hi:[1,0]
	v_mul_f32_e32 v83, 0xbfb8aa3b, v75
	v_exp_f32_e32 v83, v83
	s_nop 0
	v_add_f32_e32 v83, 1.0, v83
	v_rcp_f32_e32 v85, v83
	v_pk_mul_f32 v[76:77], v[76:77], v[82:83] op_sel_hi:[1,0]
	v_pk_mul_f32 v[66:67], v[66:67], v[82:83] op_sel_hi:[1,0]
	v_pk_mul_f32 v[70:71], v[70:71], v[82:83] op_sel_hi:[1,0]
	v_pk_mul_f32 v[74:75], v[74:75], v[84:85]
	v_pk_mul_f32 v[80:81], v[80:81], v[82:83] op_sel_hi:[1,0]
	v_pk_mul_f32 v[74:75], v[78:79], v[74:75]
	v_mul_f32_e32 v78, 0xbfb8aa3b, v76
	v_mul_f32_e32 v79, 0xbfb8aa3b, v77
	v_exp_f32_e32 v78, v78
	v_exp_f32_e32 v79, v79
	v_pk_mul_f32 v[72:73], v[72:73], v[82:83] op_sel_hi:[1,0]
	v_add_f32_e32 v78, 1.0, v78
	v_add_f32_e32 v79, 1.0, v79
	v_rcp_f32_e32 v78, v78
	v_rcp_f32_e32 v79, v79
	s_nop 0
	v_pk_mul_f32 v[76:77], v[76:77], v[78:79]
	v_mul_f32_e32 v78, 0xbfb8aa3b, v66
	v_mul_f32_e32 v79, 0xbfb8aa3b, v67
	v_exp_f32_e32 v78, v78
	v_exp_f32_e32 v79, v79
	v_pk_mul_f32 v[76:77], v[80:81], v[76:77]
	v_add_f32_e32 v78, 1.0, v78
	v_add_f32_e32 v79, 1.0, v79
	v_rcp_f32_e32 v78, v78
	v_rcp_f32_e32 v79, v79
	s_nop 0
	v_pk_mul_f32 v[66:67], v[66:67], v[78:79]
	s_nop 0
	v_pk_mul_f32 v[70:71], v[70:71], v[66:67]
	v_pk_mul_f32 v[66:67], v[68:69], v[82:83] op_sel_hi:[1,0]
	v_or_b32_e32 v78, 48, v130
	v_mul_f32_e32 v68, 0xbfb8aa3b, v66
	v_mul_f32_e32 v69, 0xbfb8aa3b, v67
	v_exp_f32_e32 v68, v68
	v_exp_f32_e32 v69, v69
	v_add_f32_e32 v68, 1.0, v68
	v_add_f32_e32 v69, 1.0, v69
	v_rcp_f32_e32 v68, v68
	v_rcp_f32_e32 v69, v69
	s_nop 0
	v_pk_mul_f32 v[66:67], v[66:67], v[68:69]
	s_nop 0
	v_pk_mul_f32 v[72:73], v[72:73], v[66:67]
	v_cvt_pk_bf16_f32 v68, v70, v71
	v_mad_i64_i32 v[70:71], s[14:15], v78, s73, v[114:115]
	v_cvt_pk_bf16_f32 v66, v74, v75
	v_cvt_pk_bf16_f32 v67, v76, v77
	v_cvt_pk_bf16_f32 v69, v72, v73
	v_lshl_add_u64 v[70:71], v[70:71], 0, v[116:117]
	global_store_dwordx4 v[70:71], v[66:69], off sc0 sc1
	ds_read2_b32 v[66:67], v131 offset0:128 offset1:144
	v_add_u32_e32 v70, 0x80, v130
	s_waitcnt lgkmcnt(0)
	v_pk_mul_f32 v[58:59], v[58:59], v[66:67] op_sel_hi:[1,0]
	s_nop 0
	v_mul_f32_e32 v68, 0xbfb8aa3b, v58
	v_mul_f32_e32 v69, 0xbfb8aa3b, v59
	v_exp_f32_e32 v68, v68
	v_exp_f32_e32 v69, v69
	v_pk_mul_f32 v[62:63], v[62:63], v[66:67] op_sel_hi:[1,0]
	v_pk_mul_f32 v[60:61], v[60:61], v[66:67] op_sel_hi:[1,0]
	v_add_f32_e32 v68, 1.0, v68
	v_add_f32_e32 v69, 1.0, v69
	v_rcp_f32_e32 v68, v68
	v_rcp_f32_e32 v69, v69
	v_pk_mul_f32 v[50:51], v[50:51], v[66:67] op_sel_hi:[1,0]
	v_pk_mul_f32 v[54:55], v[54:55], v[66:67] op_sel_hi:[1,0]
	v_pk_mul_f32 v[64:65], v[64:65], v[66:67] op_sel_hi:[1,0]
	v_pk_mul_f32 v[58:59], v[58:59], v[68:69]
	v_pk_mul_f32 v[56:57], v[56:57], v[66:67] op_sel_hi:[1,0]
	v_pk_mul_f32 v[58:59], v[62:63], v[58:59]
	v_mul_f32_e32 v62, 0xbfb8aa3b, v60
	v_mul_f32_e32 v63, 0xbfb8aa3b, v61
	v_exp_f32_e32 v62, v62
	v_exp_f32_e32 v63, v63
	v_add_f32_e32 v62, 1.0, v62
	v_add_f32_e32 v63, 1.0, v63
	v_rcp_f32_e32 v62, v62
	v_rcp_f32_e32 v63, v63
	s_nop 0
	v_pk_mul_f32 v[60:61], v[60:61], v[62:63]
	v_mul_f32_e32 v62, 0xbfb8aa3b, v50
	v_mul_f32_e32 v63, 0xbfb8aa3b, v51
	v_exp_f32_e32 v62, v62
	v_exp_f32_e32 v63, v63
	v_pk_mul_f32 v[60:61], v[64:65], v[60:61]
	v_add_f32_e32 v62, 1.0, v62
	v_add_f32_e32 v63, 1.0, v63
	v_rcp_f32_e32 v62, v62
	v_rcp_f32_e32 v63, v63
	s_nop 0
	v_pk_mul_f32 v[50:51], v[50:51], v[62:63]
	s_nop 0
	v_pk_mul_f32 v[54:55], v[54:55], v[50:51]
	v_pk_mul_f32 v[50:51], v[52:53], v[66:67] op_sel_hi:[1,0]
	s_nop 0
	v_mul_f32_e32 v52, 0xbfb8aa3b, v50
	v_mul_f32_e32 v53, 0xbfb8aa3b, v51
	v_exp_f32_e32 v52, v52
	v_exp_f32_e32 v53, v53
	v_add_f32_e32 v52, 1.0, v52
	v_add_f32_e32 v53, 1.0, v53
	v_rcp_f32_e32 v52, v52
	v_rcp_f32_e32 v53, v53
	s_nop 0
	v_pk_mul_f32 v[50:51], v[50:51], v[52:53]
	s_nop 0
	v_pk_mul_f32 v[56:57], v[56:57], v[50:51]
	v_cvt_pk_bf16_f32 v52, v54, v55
	v_mad_i64_i32 v[54:55], s[14:15], v70, s73, v[114:115]
	v_cvt_pk_bf16_f32 v50, v58, v59
	v_cvt_pk_bf16_f32 v51, v60, v61
	v_cvt_pk_bf16_f32 v53, v56, v57
	v_lshl_add_u64 v[54:55], v[54:55], 0, v[116:117]
	global_store_dwordx4 v[54:55], v[50:53], off sc0 sc1
	s_nop 1
	v_mov_b32_e32 v50, v67
	v_pk_mul_f32 v[42:43], v[42:43], v[50:51] op_sel_hi:[1,0]
	s_nop 0
	v_mul_f32_e32 v51, 0xbfb8aa3b, v42
	v_exp_f32_e32 v51, v51
	s_nop 0
	v_add_f32_e32 v51, 1.0, v51
	v_rcp_f32_e32 v52, v51
	v_pk_mul_f32 v[46:47], v[46:47], v[50:51] op_sel_hi:[1,0]
	v_mul_f32_e32 v51, 0xbfb8aa3b, v43
	v_exp_f32_e32 v51, v51
	s_nop 0
	v_add_f32_e32 v51, 1.0, v51
	v_rcp_f32_e32 v53, v51
	v_pk_mul_f32 v[44:45], v[44:45], v[50:51] op_sel_hi:[1,0]
	v_pk_mul_f32 v[34:35], v[34:35], v[50:51] op_sel_hi:[1,0]
	v_pk_mul_f32 v[38:39], v[38:39], v[50:51] op_sel_hi:[1,0]
	v_pk_mul_f32 v[42:43], v[42:43], v[52:53]
	v_pk_mul_f32 v[48:49], v[48:49], v[50:51] op_sel_hi:[1,0]
	v_pk_mul_f32 v[42:43], v[46:47], v[42:43]
	v_mul_f32_e32 v46, 0xbfb8aa3b, v44
	v_mul_f32_e32 v47, 0xbfb8aa3b, v45
	v_exp_f32_e32 v46, v46
	v_exp_f32_e32 v47, v47
	v_pk_mul_f32 v[40:41], v[40:41], v[50:51] op_sel_hi:[1,0]
	v_add_f32_e32 v46, 1.0, v46
	v_add_f32_e32 v47, 1.0, v47
	v_rcp_f32_e32 v46, v46
	v_rcp_f32_e32 v47, v47
	s_nop 0
	v_pk_mul_f32 v[44:45], v[44:45], v[46:47]
	v_mul_f32_e32 v46, 0xbfb8aa3b, v34
	v_mul_f32_e32 v47, 0xbfb8aa3b, v35
	v_exp_f32_e32 v46, v46
	v_exp_f32_e32 v47, v47
	v_pk_mul_f32 v[44:45], v[48:49], v[44:45]
	v_add_f32_e32 v46, 1.0, v46
	v_add_f32_e32 v47, 1.0, v47
	v_rcp_f32_e32 v46, v46
	v_rcp_f32_e32 v47, v47
	s_nop 0
	v_pk_mul_f32 v[34:35], v[34:35], v[46:47]
	s_nop 0
	v_pk_mul_f32 v[38:39], v[38:39], v[34:35]
	v_pk_mul_f32 v[34:35], v[36:37], v[50:51] op_sel_hi:[1,0]
	v_add_u32_e32 v46, 0x90, v130
	v_mul_f32_e32 v36, 0xbfb8aa3b, v34
	v_mul_f32_e32 v37, 0xbfb8aa3b, v35
	v_exp_f32_e32 v36, v36
	v_exp_f32_e32 v37, v37
	v_add_f32_e32 v36, 1.0, v36
	v_add_f32_e32 v37, 1.0, v37
	v_rcp_f32_e32 v36, v36
	v_rcp_f32_e32 v37, v37
	s_nop 0
	v_pk_mul_f32 v[34:35], v[34:35], v[36:37]
	s_nop 0
	v_pk_mul_f32 v[40:41], v[40:41], v[34:35]
	v_cvt_pk_bf16_f32 v36, v38, v39
	v_mad_i64_i32 v[38:39], s[14:15], v46, s73, v[114:115]
	v_cvt_pk_bf16_f32 v34, v42, v43
	v_cvt_pk_bf16_f32 v35, v44, v45
	v_cvt_pk_bf16_f32 v37, v40, v41
	v_lshl_add_u64 v[38:39], v[38:39], 0, v[116:117]
	global_store_dwordx4 v[38:39], v[34:37], off sc0 sc1
	ds_read2_b32 v[34:35], v131 offset0:160 offset1:176
	s_waitcnt lgkmcnt(0)
	v_pk_mul_f32 v[26:27], v[26:27], v[34:35] op_sel_hi:[1,0]
	s_nop 0
	v_mul_f32_e32 v36, 0xbfb8aa3b, v26
	v_mul_f32_e32 v37, 0xbfb8aa3b, v27
	v_exp_f32_e32 v36, v36
	v_exp_f32_e32 v37, v37
	v_pk_mul_f32 v[30:31], v[30:31], v[34:35] op_sel_hi:[1,0]
	v_pk_mul_f32 v[28:29], v[28:29], v[34:35] op_sel_hi:[1,0]
	v_add_f32_e32 v36, 1.0, v36
	v_add_f32_e32 v37, 1.0, v37
	v_rcp_f32_e32 v36, v36
	v_rcp_f32_e32 v37, v37
	v_pk_mul_f32 v[18:19], v[18:19], v[34:35] op_sel_hi:[1,0]
	v_pk_mul_f32 v[22:23], v[22:23], v[34:35] op_sel_hi:[1,0]
	v_pk_mul_f32 v[32:33], v[32:33], v[34:35] op_sel_hi:[1,0]
	v_pk_mul_f32 v[26:27], v[26:27], v[36:37]
	v_pk_mul_f32 v[24:25], v[24:25], v[34:35] op_sel_hi:[1,0]
	v_pk_mul_f32 v[26:27], v[30:31], v[26:27]
	v_mul_f32_e32 v30, 0xbfb8aa3b, v28
	v_mul_f32_e32 v31, 0xbfb8aa3b, v29
	v_exp_f32_e32 v30, v30
	v_exp_f32_e32 v31, v31
	v_add_f32_e32 v30, 1.0, v30
	v_add_f32_e32 v31, 1.0, v31
	v_rcp_f32_e32 v30, v30
	v_rcp_f32_e32 v31, v31
	s_nop 0
	v_pk_mul_f32 v[28:29], v[28:29], v[30:31]
	v_mul_f32_e32 v30, 0xbfb8aa3b, v18
	v_mul_f32_e32 v31, 0xbfb8aa3b, v19
	v_exp_f32_e32 v30, v30
	v_exp_f32_e32 v31, v31
	v_pk_mul_f32 v[28:29], v[32:33], v[28:29]
	v_add_f32_e32 v30, 1.0, v30
	v_add_f32_e32 v31, 1.0, v31
	v_rcp_f32_e32 v30, v30
	v_rcp_f32_e32 v31, v31
	s_nop 0
	v_pk_mul_f32 v[18:19], v[18:19], v[30:31]
	s_nop 0
	v_pk_mul_f32 v[22:23], v[22:23], v[18:19]
	v_pk_mul_f32 v[18:19], v[20:21], v[34:35] op_sel_hi:[1,0]
	v_add_u32_e32 v30, 0xa0, v130
	v_mul_f32_e32 v20, 0xbfb8aa3b, v18
	v_mul_f32_e32 v21, 0xbfb8aa3b, v19
	v_exp_f32_e32 v20, v20
	v_exp_f32_e32 v21, v21
	v_add_f32_e32 v20, 1.0, v20
	v_add_f32_e32 v21, 1.0, v21
	v_rcp_f32_e32 v20, v20
	v_rcp_f32_e32 v21, v21
	s_nop 0
	v_pk_mul_f32 v[18:19], v[18:19], v[20:21]
	s_nop 0
	v_pk_mul_f32 v[24:25], v[24:25], v[18:19]
	v_cvt_pk_bf16_f32 v20, v22, v23
	v_mad_i64_i32 v[22:23], s[14:15], v30, s73, v[114:115]
	v_cvt_pk_bf16_f32 v18, v26, v27
	v_cvt_pk_bf16_f32 v19, v28, v29
	v_cvt_pk_bf16_f32 v21, v24, v25
	v_lshl_add_u64 v[22:23], v[22:23], 0, v[116:117]
	global_store_dwordx4 v[22:23], v[18:21], off sc0 sc1
	s_nop 1
	v_mov_b32_e32 v18, v35
	v_pk_mul_f32 v[10:11], v[10:11], v[18:19] op_sel_hi:[1,0]
	s_nop 0
	v_mul_f32_e32 v19, 0xbfb8aa3b, v10
	v_exp_f32_e32 v19, v19
	s_nop 0
	v_add_f32_e32 v19, 1.0, v19
	v_rcp_f32_e32 v20, v19
	v_pk_mul_f32 v[14:15], v[14:15], v[18:19] op_sel_hi:[1,0]
	v_mul_f32_e32 v19, 0xbfb8aa3b, v11
	v_exp_f32_e32 v19, v19
	s_nop 0
	v_add_f32_e32 v19, 1.0, v19
	v_rcp_f32_e32 v21, v19
	v_pk_mul_f32 v[12:13], v[12:13], v[18:19] op_sel_hi:[1,0]
	v_pk_mul_f32 v[2:3], v[2:3], v[18:19] op_sel_hi:[1,0]
	v_pk_mul_f32 v[6:7], v[6:7], v[18:19] op_sel_hi:[1,0]
	v_pk_mul_f32 v[10:11], v[10:11], v[20:21]
	v_pk_mul_f32 v[16:17], v[16:17], v[18:19] op_sel_hi:[1,0]
	v_pk_mul_f32 v[10:11], v[14:15], v[10:11]
	v_mul_f32_e32 v14, 0xbfb8aa3b, v12
	v_mul_f32_e32 v15, 0xbfb8aa3b, v13
	v_exp_f32_e32 v14, v14
	v_exp_f32_e32 v15, v15
	v_pk_mul_f32 v[8:9], v[8:9], v[18:19] op_sel_hi:[1,0]
	v_add_f32_e32 v14, 1.0, v14
	v_add_f32_e32 v15, 1.0, v15
	v_rcp_f32_e32 v14, v14
	v_rcp_f32_e32 v15, v15
	s_nop 0
	v_pk_mul_f32 v[12:13], v[12:13], v[14:15]
	v_mul_f32_e32 v14, 0xbfb8aa3b, v2
	v_mul_f32_e32 v15, 0xbfb8aa3b, v3
	v_exp_f32_e32 v14, v14
	v_exp_f32_e32 v15, v15
	v_pk_mul_f32 v[12:13], v[16:17], v[12:13]
	v_add_f32_e32 v14, 1.0, v14
	v_add_f32_e32 v15, 1.0, v15
	v_rcp_f32_e32 v14, v14
	v_rcp_f32_e32 v15, v15
	s_nop 0
	v_pk_mul_f32 v[2:3], v[2:3], v[14:15]
	s_nop 0
	v_pk_mul_f32 v[6:7], v[6:7], v[2:3]
	v_pk_mul_f32 v[2:3], v[4:5], v[18:19] op_sel_hi:[1,0]
	v_add_u32_e32 v14, 0xb0, v130
	v_mul_f32_e32 v4, 0xbfb8aa3b, v2
	v_mul_f32_e32 v5, 0xbfb8aa3b, v3
	v_exp_f32_e32 v4, v4
	v_exp_f32_e32 v5, v5
	v_add_f32_e32 v4, 1.0, v4
	v_add_f32_e32 v5, 1.0, v5
	v_rcp_f32_e32 v4, v4
	v_rcp_f32_e32 v5, v5
	s_nop 0
	v_pk_mul_f32 v[2:3], v[2:3], v[4:5]
	s_nop 0
	v_pk_mul_f32 v[8:9], v[8:9], v[2:3]
	v_cvt_pk_bf16_f32 v4, v6, v7
	v_mad_i64_i32 v[6:7], s[14:15], v14, s73, v[114:115]
	v_cvt_pk_bf16_f32 v2, v10, v11
	v_cvt_pk_bf16_f32 v3, v12, v13
	v_cvt_pk_bf16_f32 v5, v8, v9
	v_lshl_add_u64 v[6:7], v[6:7], 0, v[116:117]
	s_mov_b64 s[14:15], -1
	global_store_dwordx4 v[6:7], v[2:5], off sc0 sc1
	s_cbranch_vccnz .LBB0_1923
	s_andn2_b64 vcc, exec, s[0:1]
	s_cbranch_vccnz .LBB0_1922
	s_barrier
	s_branch .LBB0_1922
